# static s_setprio 1 for the older wave half (waves 0-3), per-segment flips deleted
# speedup vs baseline: 1.0096x; 1.0096x over previous
; template <class Epi>
; __device__ __forceinline__ void gemm_phase(LAS unsigned char* lds, const Gemm g, const StaticOrder S, const Epi E) {
;     const int tid = threadIdx.x, wid = __builtin_amdgcn_readfirstlane(tid >> 6), lane = tid & 63, wr = wid >> 2, wc = wid & 3, fr = lane & 15, fq = lane >> 4;
_Z8mega_fwd6Params:
	v_readfirstlane_b32 s100, v0
	s_nop 3
	s_and_b32 s100, s100, 0x3ff
	s_lshr_b32 s100, s100, 6
	s_cmp_lt_u32 s100, 4
	s_cbranch_scc0 .Lprio_done
	s_setprio 1
